# hot loop heads (four GEMM K-loops, mix conv loop, both scan loops, attention loop) aligned to 64 bytes with s_nop fill
# baseline (speedup 1.0000x reference)
; template <class Epi, class Sched>
; __device__ __forceinline__ void gemm_phase(LAS unsigned char* lds, const Gemm g, const Sched& S, const Epi& E) {
;     ...
;     for (;;) {
;         const bool has_next = S.next(ui + 1, nxt);
;         const char* nA = has_next ? (const char*)g.A + (size_t)nxt.pm * tA : cA; const char* nB = has_next ? (const char*)g.Bt + (size_t)nxt.pn * tB : cB;
;         for (int t = 0; t < nt; t += 2) {
;             const bool last = (t == nt - 2);
;             const char* a1 = cA + (size_t)(t + 1) * kstep;
;             const char* a2 = last ? nA : cA + (size_t)(t + 2) * kstep; const char* b2 = last ? nB : cB + (size_t)(t + 2) * kstep;
;     ...
;         for (int a = 0; a < 2; ++a)
; #pragma unroll
;             for (int b = 0; b < 2; ++b)
; #pragma unroll
;                 for (int m = 0; m < 4; ++m)
; #pragma unroll
;                     for (int n = 0; n < 2; ++n) acc[a][b][m][n] = (f32x4){0.f, 0.f, 0.f, 0.f};
;         cur = nxt; cA = nA; cB = nB; ++ui;
.LBB0_73:
	s_mov_b32 s14, s37
	s_add_i32 s37, s38, 1
	s_cmp_lt_u32 s38, 11
	s_cselect_b64 s[12:13], -1, 0
	s_and_b64 s[8:9], s[12:13], exec
	s_cselect_b32 s8, s37, s14
	s_ashr_i32 s9, s8, 31
	s_lshl_b64 s[8:9], s[8:9], 19
	s_add_u32 s8, s4, s8
	s_addc_u32 s9, s5, s9
	s_and_b64 s[12:13], s[12:13], exec
	s_cselect_b32 s39, s9, s11
	s_cselect_b32 s40, s8, s10
	s_add_u32 s41, s10, 0x100
	v_mov_b32_e32 v0, 0
	s_addc_u32 s42, s11, 0
	s_mov_b32 s43, -2
	s_mov_b64 s[10:11], s[6:7]
	v_mov_b32_e32 v1, v0
	v_mov_b32_e32 v2, v0
	v_mov_b32_e32 v3, v0
	v_mov_b32_e32 v4, v0
	v_mov_b32_e32 v5, v0
	v_mov_b32_e32 v6, v0
	v_mov_b32_e32 v7, v0
	v_mov_b32_e32 v8, v0
	v_mov_b32_e32 v9, v0
	v_mov_b32_e32 v10, v0
	v_mov_b32_e32 v11, v0
	v_mov_b32_e32 v16, v0
	v_mov_b32_e32 v17, v0
	v_mov_b32_e32 v18, v0
	v_mov_b32_e32 v19, v0
	v_mov_b32_e32 v24, v0
	v_mov_b32_e32 v25, v0
	v_mov_b32_e32 v26, v0
	v_mov_b32_e32 v27, v0
	v_mov_b32_e32 v32, v0
	v_mov_b32_e32 v33, v0
	v_mov_b32_e32 v34, v0
	v_mov_b32_e32 v35, v0
	v_mov_b32_e32 v40, v0
	v_mov_b32_e32 v41, v0
	v_mov_b32_e32 v42, v0
	v_mov_b32_e32 v43, v0
	v_mov_b32_e32 v48, v0
	v_mov_b32_e32 v49, v0
	v_mov_b32_e32 v50, v0
	v_mov_b32_e32 v51, v0
	v_mov_b32_e32 v12, v0
	v_mov_b32_e32 v13, v0
	v_mov_b32_e32 v14, v0
	v_mov_b32_e32 v15, v0
	v_mov_b32_e32 v20, v0
	v_mov_b32_e32 v21, v0
	v_mov_b32_e32 v22, v0
	v_mov_b32_e32 v23, v0
	v_mov_b32_e32 v28, v0
	v_mov_b32_e32 v29, v0
	v_mov_b32_e32 v30, v0
	v_mov_b32_e32 v31, v0
	v_mov_b32_e32 v36, v0
	v_mov_b32_e32 v37, v0
	v_mov_b32_e32 v38, v0
	v_mov_b32_e32 v39, v0
	v_mov_b32_e32 v44, v0
	v_mov_b32_e32 v45, v0
	v_mov_b32_e32 v46, v0
	v_mov_b32_e32 v47, v0
	v_mov_b32_e32 v52, v0
	v_mov_b32_e32 v53, v0
	v_mov_b32_e32 v54, v0
	v_mov_b32_e32 v55, v0
	v_mov_b32_e32 v56, v0
	v_mov_b32_e32 v57, v0
	v_mov_b32_e32 v58, v0
	v_mov_b32_e32 v59, v0
	v_mov_b32_e32 v60, v0
	v_mov_b32_e32 v61, v0
	v_mov_b32_e32 v62, v0
	v_mov_b32_e32 v63, v0
	v_mov_b32_e32 v64, v0
	v_mov_b32_e32 v65, v0
	v_mov_b32_e32 v66, v0
	v_mov_b32_e32 v67, v0
	v_mov_b32_e32 v68, v0
	v_mov_b32_e32 v69, v0
	v_mov_b32_e32 v70, v0
	v_mov_b32_e32 v71, v0
	v_mov_b32_e32 v72, v0
	v_mov_b32_e32 v73, v0
	v_mov_b32_e32 v74, v0
	v_mov_b32_e32 v75, v0
	v_mov_b32_e32 v80, v0
	v_mov_b32_e32 v81, v0
	v_mov_b32_e32 v82, v0
	v_mov_b32_e32 v83, v0
	v_mov_b32_e32 v88, v0
	v_mov_b32_e32 v89, v0
	v_mov_b32_e32 v90, v0
	v_mov_b32_e32 v91, v0
	v_mov_b32_e32 v96, v0
	v_mov_b32_e32 v97, v0
	v_mov_b32_e32 v98, v0
	v_mov_b32_e32 v99, v0
	v_mov_b32_e32 v104, v0
	v_mov_b32_e32 v105, v0
	v_mov_b32_e32 v106, v0
	v_mov_b32_e32 v107, v0
	v_mov_b32_e32 v112, v0
	v_mov_b32_e32 v113, v0
	v_mov_b32_e32 v114, v0
	v_mov_b32_e32 v115, v0
	v_mov_b32_e32 v76, v0
	v_mov_b32_e32 v77, v0
	v_mov_b32_e32 v78, v0
	v_mov_b32_e32 v79, v0
	v_mov_b32_e32 v84, v0
	v_mov_b32_e32 v85, v0
	v_mov_b32_e32 v86, v0
	v_mov_b32_e32 v87, v0
	v_mov_b32_e32 v92, v0
	v_mov_b32_e32 v93, v0
	v_mov_b32_e32 v94, v0
	v_mov_b32_e32 v95, v0
	v_mov_b32_e32 v100, v0
	v_mov_b32_e32 v101, v0
	v_mov_b32_e32 v102, v0
	v_mov_b32_e32 v103, v0
	v_mov_b32_e32 v108, v0
	v_mov_b32_e32 v109, v0
	v_mov_b32_e32 v110, v0
	v_mov_b32_e32 v111, v0
	v_mov_b32_e32 v116, v0
	v_mov_b32_e32 v117, v0
	v_mov_b32_e32 v118, v0
	v_mov_b32_e32 v119, v0
	v_mov_b32_e32 v120, v0
	v_mov_b32_e32 v121, v0
	v_mov_b32_e32 v122, v0
	v_mov_b32_e32 v123, v0
	v_mov_b32_e32 v124, v0
	v_mov_b32_e32 v125, v0
	v_mov_b32_e32 v126, v0
	v_mov_b32_e32 v127, v0
	.p2alignl 6, 3212836864

; __device__ __forceinline__ unsigned cvt_pk(float lo, float hi) { unsigned r; asm volatile("v_cvt_pk_bf16_f32 %0, %1, %2" : "=v"(r) : "v"(lo), "v"(hi)); return r; }
; template <int NB> __device__ __forceinline__ void mm16(f32x4 (&acc)[NB], const unsigned char* Xs, const bf16x8 (&yf)[4], int lane) {
;     const int i = lane & 15, kq = lane >> 4;
; #pragma unroll
;     for (int ks = 0; ks < 4; ++ks)
; #pragma unroll
;         for (int nb = 0; nb < NB; ++nb) {
;             const bf16x8 x = *(const bf16x8*)(Xs + swz(nb * 16 + i, ks * 4 + kq));
;             acc[nb] = __builtin_amdgcn_mfma_f32_16x16x32_bf16(x, yf[ks], acc[nb], 0, 0, 0);
;             if ((nb & 3) == 3) __builtin_amdgcn_sched_barrier(0);
;         }
; __device__ void phase_mix(const Params& p, unsigned char* smem) {
;     ...
;             bf16x8 af[4]; ldfrag(af, As, wid, lane);
;             const size_t r = (size_t)r0 + wid * 16 + li;
; #pragma unroll
;             for (int which = 0; which < 2; ++which) {
;                 f32x4 acc[8];
; #pragma unroll
;                 for (int nb = 0; nb < 8; ++nb) acc[nb] = (f32x4){0.f, 0.f, 0.f, 0.f};
;                 mm16<8>(acc, which ? B2s : Bs, af, lane);
;                 bf16_t* O = which ? K0 : Q0;
; #pragma unroll
;                 for (int nb = 0; nb < 8; ++nb) { u32x2 o; o.x = cvt_pk(acc[nb][0], acc[nb][1]); o.y = cvt_pk(acc[nb][2], acc[nb][3]);
;                     *(u32x2*)(O + r * 512 + h * 128 + nb * 16 + kq * 4) = o; }
;             }
.LBB0_199:
	s_or_b64 exec, exec, s[6:7]
	v_add_u32_e32 v158, v108, v104
	ds_read_b128 v[80:83], v158 offset:32768
	ds_read_b128 v[118:121], v158 offset:36864
	ds_read_b128 v[122:125], v114
	ds_read_b128 v[126:129], v115
	ds_read_b128 v[134:137], v158 offset:40960
	v_lshl_add_u64 v[102:103], v[94:95], 0, s[0:1]
	v_lshlrev_b64 v[102:103], 10, v[102:103]
	s_waitcnt lgkmcnt(2)
	v_mfma_f32_16x16x32_bf16 v[130:133], v[80:83], v[122:125], 0
	ds_read_b128 v[138:141], v158 offset:45056
	ds_read_b128 v[142:145], v116
	ds_read_b128 v[80:83], v117
	v_lshl_add_u64 v[102:103], v[96:97], 0, v[102:103]
	v_mfma_f32_16x16x32_bf16 v[118:121], v[118:121], v[122:125], 0
	s_waitcnt lgkmcnt(3)
	v_mfma_f32_16x16x32_bf16 v[134:137], v[134:137], v[122:125], 0
	s_waitcnt lgkmcnt(2)
	v_mfma_f32_16x16x32_bf16 v[138:141], v[138:141], v[122:125], 0
	ds_read_b128 v[146:149], v158 offset:49152
	ds_read_b128 v[150:153], v158 offset:53248
	ds_read_b128 v[154:157], v158 offset:57344
	ds_read_b128 v[158:161], v158 offset:61440
	s_waitcnt lgkmcnt(3)
	v_mfma_f32_16x16x32_bf16 v[146:149], v[146:149], v[122:125], 0
	s_waitcnt lgkmcnt(2)
	v_mfma_f32_16x16x32_bf16 v[150:153], v[150:153], v[122:125], 0
	s_waitcnt lgkmcnt(1)
	v_mfma_f32_16x16x32_bf16 v[154:157], v[154:157], v[122:125], 0
	s_waitcnt lgkmcnt(0)
	v_mfma_f32_16x16x32_bf16 v[158:161], v[158:161], v[122:125], 0
	v_add_u32_e32 v171, v108, v105
	ds_read_b128 v[162:165], v171 offset:32768
	ds_read_b128 v[166:169], v171 offset:36864
	s_waitcnt lgkmcnt(1)
	v_mfma_f32_16x16x32_bf16 v[130:133], v[162:165], v[126:129], v[130:133]
	ds_read_b128 v[162:165], v171 offset:40960
	s_waitcnt lgkmcnt(1)
	v_mfma_f32_16x16x32_bf16 v[118:121], v[166:169], v[126:129], v[118:121]
	ds_read_b128 v[166:169], v171 offset:45056
	s_waitcnt lgkmcnt(1)
	v_mfma_f32_16x16x32_bf16 v[134:137], v[162:165], v[126:129], v[134:137]
	s_waitcnt lgkmcnt(0)
	v_mfma_f32_16x16x32_bf16 v[138:141], v[166:169], v[126:129], v[138:141]
	ds_read_b128 v[162:165], v171 offset:49152
	ds_read_b128 v[166:169], v171 offset:53248
	s_waitcnt lgkmcnt(1)
	v_mfma_f32_16x16x32_bf16 v[146:149], v[162:165], v[126:129], v[146:149]
	ds_read_b128 v[162:165], v171 offset:57344
	s_waitcnt lgkmcnt(1)
	v_mfma_f32_16x16x32_bf16 v[150:153], v[166:169], v[126:129], v[150:153]
	ds_read_b128 v[166:169], v171 offset:61440
	s_waitcnt lgkmcnt(1)
	v_mfma_f32_16x16x32_bf16 v[154:157], v[162:165], v[126:129], v[154:157]
	s_waitcnt lgkmcnt(0)
	v_mfma_f32_16x16x32_bf16 v[158:161], v[166:169], v[126:129], v[158:161]
	v_add_u32_e32 v171, v108, v106
	ds_read_b128 v[162:165], v171 offset:32768
	ds_read_b128 v[166:169], v171 offset:36864
	s_waitcnt lgkmcnt(1)
	v_mfma_f32_16x16x32_bf16 v[130:133], v[162:165], v[142:145], v[130:133]
	ds_read_b128 v[162:165], v171 offset:40960
	s_waitcnt lgkmcnt(1)
	v_mfma_f32_16x16x32_bf16 v[118:121], v[166:169], v[142:145], v[118:121]
	ds_read_b128 v[166:169], v171 offset:45056
	s_waitcnt lgkmcnt(1)
	v_mfma_f32_16x16x32_bf16 v[134:137], v[162:165], v[142:145], v[134:137]
	s_waitcnt lgkmcnt(0)
	v_mfma_f32_16x16x32_bf16 v[138:141], v[166:169], v[142:145], v[138:141]
	ds_read_b128 v[162:165], v171 offset:49152
	ds_read_b128 v[166:169], v171 offset:53248
	s_waitcnt lgkmcnt(1)
	v_mfma_f32_16x16x32_bf16 v[146:149], v[162:165], v[142:145], v[146:149]
	ds_read_b128 v[162:165], v171 offset:57344
	s_waitcnt lgkmcnt(1)
	v_mfma_f32_16x16x32_bf16 v[150:153], v[166:169], v[142:145], v[150:153]
	ds_read_b128 v[166:169], v171 offset:61440
	s_waitcnt lgkmcnt(1)
	v_mfma_f32_16x16x32_bf16 v[154:157], v[162:165], v[142:145], v[154:157]
	s_waitcnt lgkmcnt(0)
	v_mfma_f32_16x16x32_bf16 v[158:161], v[166:169], v[142:145], v[158:161]
	v_add_u32_e32 v171, v108, v107
	ds_read_b128 v[162:165], v171 offset:32768
	ds_read_b128 v[166:169], v171 offset:36864
	s_waitcnt lgkmcnt(1)
	v_mfma_f32_16x16x32_bf16 v[130:133], v[162:165], v[80:83], v[130:133]
	ds_read_b128 v[162:165], v171 offset:40960
	s_waitcnt lgkmcnt(1)
	v_mfma_f32_16x16x32_bf16 v[118:121], v[166:169], v[80:83], v[118:121]
	ds_read_b128 v[166:169], v171 offset:45056
	s_waitcnt lgkmcnt(1)
	v_mfma_f32_16x16x32_bf16 v[134:137], v[162:165], v[80:83], v[134:137]
	s_waitcnt lgkmcnt(0)
	v_mfma_f32_16x16x32_bf16 v[138:141], v[166:169], v[80:83], v[138:141]
	ds_read_b128 v[162:165], v171 offset:49152
	ds_read_b128 v[166:169], v171 offset:53248
	s_waitcnt lgkmcnt(1)
	v_mfma_f32_16x16x32_bf16 v[146:149], v[162:165], v[80:83], v[146:149]
	ds_read_b128 v[162:165], v171 offset:57344
	s_waitcnt lgkmcnt(1)
	v_mfma_f32_16x16x32_bf16 v[150:153], v[166:169], v[80:83], v[150:153]
	ds_read_b128 v[166:169], v171 offset:61440
	s_waitcnt lgkmcnt(1)
	v_mfma_f32_16x16x32_bf16 v[154:157], v[162:165], v[80:83], v[154:157]
	s_waitcnt lgkmcnt(0)
	v_mfma_f32_16x16x32_bf16 v[158:161], v[166:169], v[80:83], v[158:161]
	v_cvt_pk_bf16_f32 v130, v130, v131
	v_cvt_pk_bf16_f32 v131, v132, v133
	global_store_dwordx2 v[102:103], v[130:131], off
	v_cvt_pk_bf16_f32 v118, v118, v119
	v_cvt_pk_bf16_f32 v119, v120, v121
	global_store_dwordx2 v[102:103], v[118:119], off offset:32
	v_cvt_pk_bf16_f32 v118, v134, v135
	v_cvt_pk_bf16_f32 v119, v136, v137
	global_store_dwordx2 v[102:103], v[118:119], off offset:64
	v_cvt_pk_bf16_f32 v118, v138, v139
	v_cvt_pk_bf16_f32 v119, v140, v141
	global_store_dwordx2 v[102:103], v[118:119], off offset:96
	v_cvt_pk_bf16_f32 v118, v146, v147
	v_cvt_pk_bf16_f32 v119, v148, v149
	global_store_dwordx2 v[102:103], v[118:119], off offset:128
	v_cvt_pk_bf16_f32 v118, v150, v151
	v_cvt_pk_bf16_f32 v119, v152, v153
	global_store_dwordx2 v[102:103], v[118:119], off offset:160
	v_cvt_pk_bf16_f32 v118, v154, v155
	v_cvt_pk_bf16_f32 v119, v156, v157
	global_store_dwordx2 v[102:103], v[118:119], off offset:192
	v_cvt_pk_bf16_f32 v146, v158, v159
	s_nop 0
	v_add_u32_e32 v158, v109, v104
	v_cvt_pk_bf16_f32 v147, v160, v161
	ds_read_b128 v[118:121], v158
	ds_read_b128 v[130:133], v158 offset:4096
	ds_read_b128 v[134:137], v158 offset:8192
	ds_read_b128 v[138:141], v158 offset:12288
	s_waitcnt lgkmcnt(3)
; __device__ __forceinline__ unsigned cvt_pk(float lo, float hi) { unsigned r; asm volatile("v_cvt_pk_bf16_f32 %0, %1, %2" : "=v"(r) : "v"(lo), "v"(hi)); return r; }
; __device__ void phase_mix(const Params& p, unsigned char* smem) {
;     ...
;             bf16x8 af[4]; ldfrag(af, As, wid, lane);
;             const size_t r = (size_t)r0 + wid * 16 + li;
; #pragma unroll
;             for (int which = 0; which < 2; ++which) {
;                 f32x4 acc[8];
; #pragma unroll
;                 for (int nb = 0; nb < 8; ++nb) acc[nb] = (f32x4){0.f, 0.f, 0.f, 0.f};
;                 mm16<8>(acc, which ? B2s : Bs, af, lane);
;                 bf16_t* O = which ? K0 : Q0;
; #pragma unroll
;                 for (int nb = 0; nb < 8; ++nb) { u32x2 o; o.x = cvt_pk(acc[nb][0], acc[nb][1]); o.y = cvt_pk(acc[nb][2], acc[nb][3]);
;                     *(u32x2*)(O + r * 512 + h * 128 + nb * 16 + kq * 4) = o; }
;             }
;             __syncthreads();
	v_mfma_f32_16x16x32_bf16 v[118:121], v[118:121], v[122:125], 0
	global_store_dwordx2 v[102:103], v[146:147], off offset:224
	s_waitcnt lgkmcnt(2)
	v_mfma_f32_16x16x32_bf16 v[130:133], v[130:133], v[122:125], 0
	s_waitcnt lgkmcnt(1)
	v_mfma_f32_16x16x32_bf16 v[134:137], v[134:137], v[122:125], 0
	s_waitcnt lgkmcnt(0)
	v_mfma_f32_16x16x32_bf16 v[138:141], v[138:141], v[122:125], 0
	ds_read_b128 v[146:149], v158 offset:16384
	ds_read_b128 v[150:153], v158 offset:20480
	ds_read_b128 v[154:157], v158 offset:24576
	ds_read_b128 v[158:161], v158 offset:28672
	s_waitcnt lgkmcnt(3)
	v_mfma_f32_16x16x32_bf16 v[146:149], v[146:149], v[122:125], 0
	s_waitcnt lgkmcnt(2)
	v_mfma_f32_16x16x32_bf16 v[150:153], v[150:153], v[122:125], 0
	s_waitcnt lgkmcnt(1)
	v_mfma_f32_16x16x32_bf16 v[154:157], v[154:157], v[122:125], 0
	s_waitcnt lgkmcnt(0)
	v_mfma_f32_16x16x32_bf16 v[122:125], v[158:161], v[122:125], 0
	v_add_u32_e32 v166, v109, v105
	ds_read_b128 v[158:161], v166
	ds_read_b128 v[162:165], v166 offset:4096
	s_waitcnt lgkmcnt(1)
	v_mfma_f32_16x16x32_bf16 v[118:121], v[158:161], v[126:129], v[118:121]
	ds_read_b128 v[158:161], v166 offset:8192
	s_waitcnt lgkmcnt(1)
	v_mfma_f32_16x16x32_bf16 v[130:133], v[162:165], v[126:129], v[130:133]
	ds_read_b128 v[162:165], v166 offset:12288
	s_waitcnt lgkmcnt(1)
	v_mfma_f32_16x16x32_bf16 v[134:137], v[158:161], v[126:129], v[134:137]
	s_waitcnt lgkmcnt(0)
	v_mfma_f32_16x16x32_bf16 v[138:141], v[162:165], v[126:129], v[138:141]
	ds_read_b128 v[158:161], v166 offset:16384
	ds_read_b128 v[162:165], v166 offset:20480
	s_waitcnt lgkmcnt(1)
	v_mfma_f32_16x16x32_bf16 v[146:149], v[158:161], v[126:129], v[146:149]
	ds_read_b128 v[158:161], v166 offset:24576
	s_waitcnt lgkmcnt(1)
	v_mfma_f32_16x16x32_bf16 v[150:153], v[162:165], v[126:129], v[150:153]
	ds_read_b128 v[162:165], v166 offset:28672
	s_waitcnt lgkmcnt(1)
	v_mfma_f32_16x16x32_bf16 v[154:157], v[158:161], v[126:129], v[154:157]
	s_waitcnt lgkmcnt(0)
	v_mfma_f32_16x16x32_bf16 v[122:125], v[162:165], v[126:129], v[122:125]
	v_add_u32_e32 v162, v109, v106
	ds_read_b128 v[126:129], v162
	ds_read_b128 v[158:161], v162 offset:4096
	s_waitcnt lgkmcnt(1)
	v_mfma_f32_16x16x32_bf16 v[118:121], v[126:129], v[142:145], v[118:121]
	ds_read_b128 v[126:129], v162 offset:8192
	s_waitcnt lgkmcnt(1)
	v_mfma_f32_16x16x32_bf16 v[130:133], v[158:161], v[142:145], v[130:133]
	ds_read_b128 v[158:161], v162 offset:12288
	s_waitcnt lgkmcnt(1)
	v_mfma_f32_16x16x32_bf16 v[126:129], v[126:129], v[142:145], v[134:137]
	s_waitcnt lgkmcnt(0)
	v_mfma_f32_16x16x32_bf16 v[134:137], v[158:161], v[142:145], v[138:141]
	s_nop 2
	ds_read_b128 v[138:141], v162 offset:16384
	ds_read_b128 v[158:161], v162 offset:20480
	s_waitcnt lgkmcnt(1)
	v_mfma_f32_16x16x32_bf16 v[138:141], v[138:141], v[142:145], v[146:149]
	s_nop 2
	ds_read_b128 v[146:149], v162 offset:24576
	s_waitcnt lgkmcnt(1)
	v_mfma_f32_16x16x32_bf16 v[150:153], v[158:161], v[142:145], v[150:153]
	ds_read_b128 v[158:161], v162 offset:28672
	s_waitcnt lgkmcnt(1)
	v_mfma_f32_16x16x32_bf16 v[146:149], v[146:149], v[142:145], v[154:157]
	s_waitcnt lgkmcnt(0)
	v_mfma_f32_16x16x32_bf16 v[122:125], v[158:161], v[142:145], v[122:125]
	v_add_u32_e32 v158, v109, v107
	ds_read_b128 v[142:145], v158
	ds_read_b128 v[154:157], v158 offset:4096
	s_waitcnt lgkmcnt(1)
	v_mfma_f32_16x16x32_bf16 v[118:121], v[142:145], v[80:83], v[118:121]
	ds_read_b128 v[142:145], v158 offset:8192
	s_waitcnt lgkmcnt(1)
	v_mfma_f32_16x16x32_bf16 v[130:133], v[154:157], v[80:83], v[130:133]
	ds_read_b128 v[154:157], v158 offset:12288
	s_waitcnt lgkmcnt(1)
	v_mfma_f32_16x16x32_bf16 v[126:129], v[142:145], v[80:83], v[126:129]
	s_waitcnt lgkmcnt(0)
	v_mfma_f32_16x16x32_bf16 v[134:137], v[154:157], v[80:83], v[134:137]
	ds_read_b128 v[142:145], v158 offset:16384
	ds_read_b128 v[154:157], v158 offset:20480
	s_waitcnt lgkmcnt(1)
	v_mfma_f32_16x16x32_bf16 v[138:141], v[142:145], v[80:83], v[138:141]
	ds_read_b128 v[142:145], v158 offset:24576
	s_waitcnt lgkmcnt(1)
	v_mfma_f32_16x16x32_bf16 v[150:153], v[154:157], v[80:83], v[150:153]
	ds_read_b128 v[154:157], v158 offset:28672
	s_waitcnt lgkmcnt(1)
	v_mfma_f32_16x16x32_bf16 v[142:145], v[142:145], v[80:83], v[146:149]
	s_waitcnt lgkmcnt(0)
	v_mfma_f32_16x16x32_bf16 v[80:83], v[154:157], v[80:83], v[122:125]
	v_add_co_u32_e32 v102, vcc, s14, v102
	v_cvt_pk_bf16_f32 v118, v118, v119
	v_cvt_pk_bf16_f32 v119, v120, v121
	s_add_i32 s0, s0, s10
	s_nop 0
	v_addc_co_u32_e32 v103, vcc, 0, v103, vcc
	global_store_dwordx2 v[102:103], v[118:119], off
	v_cvt_pk_bf16_f32 v118, v130, v131
	v_cvt_pk_bf16_f32 v119, v132, v133
	global_store_dwordx2 v[102:103], v[118:119], off offset:32
	v_cvt_pk_bf16_f32 v118, v126, v127
	v_cvt_pk_bf16_f32 v119, v128, v129
	global_store_dwordx2 v[102:103], v[118:119], off offset:64
	v_cvt_pk_bf16_f32 v118, v134, v135
	v_cvt_pk_bf16_f32 v119, v136, v137
	global_store_dwordx2 v[102:103], v[118:119], off offset:96
	v_cvt_pk_bf16_f32 v118, v138, v139
	v_cvt_pk_bf16_f32 v119, v140, v141
	global_store_dwordx2 v[102:103], v[118:119], off offset:128
	v_cvt_pk_bf16_f32 v118, v150, v151
	v_cvt_pk_bf16_f32 v119, v152, v153
	s_andn2_b64 vcc, exec, s[4:5]
	global_store_dwordx2 v[102:103], v[118:119], off offset:160
	v_cvt_pk_bf16_f32 v118, v142, v143
	v_cvt_pk_bf16_f32 v119, v144, v145
	global_store_dwordx2 v[102:103], v[118:119], off offset:192
	v_cvt_pk_bf16_f32 v80, v80, v81
	v_cvt_pk_bf16_f32 v81, v82, v83
	global_store_dwordx2 v[102:103], v[80:81], off offset:224
	s_barrier
	s_cbranch_vccz .LBB0_224
	.p2alignl 6, 3212836864

; template <int SPLIT> __device__ __forceinline__ void scan_item(const Params& p, unsigned char* smem, const int item, const int vh) {
;     ...
;         for (int j = 0; j < nc; ++j) {
;             const int jn = (j + 1 < nc) ? j + 1 : j;
.LBB0_289:
	s_or_b64 exec, exec, s[86:87]
	v_add_co_u32_e64 v80, s[4:5], s95, 1
	v_add_u32_e32 v152, s93, v152
	v_readfirstlane_b32 s95, v80
	s_andn2_b64 vcc, exec, s[4:5]
	s_cbranch_vccz .LBB0_296
	.p2alignl 6, 3212836864

; template <int SPLIT> __device__ __forceinline__ void scan_item(const Params& p, unsigned char* smem, const int item, const int vh) {
;     ...
;         for (int j = 0; j < nc; ++j) {
;             const int jn = (j + 1 < nc) ? j + 1 : j;
.LBB0_311:
	s_or_b64 exec, exec, s[86:87]
	v_add_co_u32_e64 v67, s[4:5], s93, 1
	v_add_u32_e32 v131, s91, v131
	v_readfirstlane_b32 s93, v67
	s_andn2_b64 vcc, exec, s[4:5]
	s_cbranch_vccz .LBB0_318
	.p2alignl 6, 3212836864

; template <class Epi, class Sched>
; __device__ __forceinline__ void gemm_phase(LAS unsigned char* lds, const Gemm g, const Sched& S, const Epi& E) {
;     ...
;     for (;;) {
;         const bool has_next = S.next(ui + 1, nxt);
;         const char* nA = has_next ? (const char*)g.A + (size_t)nxt.pm * tA : cA; const char* nB = has_next ? (const char*)g.Bt + (size_t)nxt.pn * tB : cB;
;         for (int t = 0; t < nt; t += 2) {
;             const bool last = (t == nt - 2);
;             const char* a1 = cA + (size_t)(t + 1) * kstep;
;             const char* a2 = last ? nA : cA + (size_t)(t + 2) * kstep; const char* b2 = last ? nB : cB + (size_t)(t + 2) * kstep;
;     ...
;         for (int a = 0; a < 2; ++a)
; #pragma unroll
;             for (int b = 0; b < 2; ++b)
; #pragma unroll
;                 for (int m = 0; m < 4; ++m)
; #pragma unroll
;                     for (int n = 0; n < 2; ++n) acc[a][b][m][n] = (f32x4){0.f, 0.f, 0.f, 0.f};
;         cur = nxt; cA = nA; cB = nB; ++ui;
.LBB0_376:
	s_mov_b32 s18, s42
	s_add_i32 s42, s43, 1
	s_cmp_lt_u32 s43, 3
	s_cselect_b64 s[16:17], -1, 0
	s_and_b64 s[12:13], s[16:17], exec
	s_cselect_b32 s12, s42, s18
	s_ashr_i32 s13, s12, 31
	s_lshl_b64 s[12:13], s[12:13], 19
	s_add_u32 s12, s0, s12
	s_addc_u32 s13, s1, s13
	s_and_b64 s[16:17], s[16:17], exec
	s_cselect_b32 s44, s13, s15
	s_cselect_b32 s45, s12, s14
	s_add_u32 s46, s14, 0x100
	v_mov_b32_e32 v0, 0
	s_addc_u32 s47, s15, 0
	s_mov_b32 s48, -2
	s_mov_b64 s[14:15], s[10:11]
	v_mov_b32_e32 v1, v0
	v_mov_b32_e32 v2, v0
	v_mov_b32_e32 v3, v0
	v_mov_b32_e32 v4, v0
	v_mov_b32_e32 v5, v0
	v_mov_b32_e32 v6, v0
	v_mov_b32_e32 v7, v0
	v_mov_b32_e32 v8, v0
	v_mov_b32_e32 v9, v0
	v_mov_b32_e32 v10, v0
	v_mov_b32_e32 v11, v0
	v_mov_b32_e32 v16, v0
	v_mov_b32_e32 v17, v0
	v_mov_b32_e32 v18, v0
	v_mov_b32_e32 v19, v0
	v_mov_b32_e32 v24, v0
	v_mov_b32_e32 v25, v0
	v_mov_b32_e32 v26, v0
	v_mov_b32_e32 v27, v0
	v_mov_b32_e32 v32, v0
	v_mov_b32_e32 v33, v0
	v_mov_b32_e32 v34, v0
	v_mov_b32_e32 v35, v0
	v_mov_b32_e32 v40, v0
	v_mov_b32_e32 v41, v0
	v_mov_b32_e32 v42, v0
	v_mov_b32_e32 v43, v0
	v_mov_b32_e32 v48, v0
	v_mov_b32_e32 v49, v0
	v_mov_b32_e32 v50, v0
	v_mov_b32_e32 v51, v0
	v_mov_b32_e32 v12, v0
	v_mov_b32_e32 v13, v0
	v_mov_b32_e32 v14, v0
	v_mov_b32_e32 v15, v0
	v_mov_b32_e32 v20, v0
	v_mov_b32_e32 v21, v0
	v_mov_b32_e32 v22, v0
	v_mov_b32_e32 v23, v0
	v_mov_b32_e32 v28, v0
	v_mov_b32_e32 v29, v0
	v_mov_b32_e32 v30, v0
	v_mov_b32_e32 v31, v0
	v_mov_b32_e32 v36, v0
	v_mov_b32_e32 v37, v0
	v_mov_b32_e32 v38, v0
	v_mov_b32_e32 v39, v0
	v_mov_b32_e32 v44, v0
	v_mov_b32_e32 v45, v0
	v_mov_b32_e32 v46, v0
	v_mov_b32_e32 v47, v0
	v_mov_b32_e32 v52, v0
	v_mov_b32_e32 v53, v0
	v_mov_b32_e32 v54, v0
	v_mov_b32_e32 v55, v0
	v_mov_b32_e32 v56, v0
	v_mov_b32_e32 v57, v0
	v_mov_b32_e32 v58, v0
	v_mov_b32_e32 v59, v0
	v_mov_b32_e32 v60, v0
	v_mov_b32_e32 v61, v0
	v_mov_b32_e32 v62, v0
	v_mov_b32_e32 v63, v0
	v_mov_b32_e32 v64, v0
	v_mov_b32_e32 v65, v0
	v_mov_b32_e32 v66, v0
	v_mov_b32_e32 v67, v0
	v_mov_b32_e32 v68, v0
	v_mov_b32_e32 v69, v0
	v_mov_b32_e32 v70, v0
	v_mov_b32_e32 v71, v0
	v_mov_b32_e32 v72, v0
	v_mov_b32_e32 v73, v0
	v_mov_b32_e32 v74, v0
	v_mov_b32_e32 v75, v0
	v_mov_b32_e32 v80, v0
	v_mov_b32_e32 v81, v0
	v_mov_b32_e32 v82, v0
	v_mov_b32_e32 v83, v0
	v_mov_b32_e32 v88, v0
	v_mov_b32_e32 v89, v0
	v_mov_b32_e32 v90, v0
	v_mov_b32_e32 v91, v0
	v_mov_b32_e32 v96, v0
	v_mov_b32_e32 v97, v0
	v_mov_b32_e32 v98, v0
	v_mov_b32_e32 v99, v0
	v_mov_b32_e32 v104, v0
	v_mov_b32_e32 v105, v0
	v_mov_b32_e32 v106, v0
	v_mov_b32_e32 v107, v0
	v_mov_b32_e32 v112, v0
	v_mov_b32_e32 v113, v0
	v_mov_b32_e32 v114, v0
	v_mov_b32_e32 v115, v0
	v_mov_b32_e32 v76, v0
	v_mov_b32_e32 v77, v0
	v_mov_b32_e32 v78, v0
	v_mov_b32_e32 v79, v0
	v_mov_b32_e32 v84, v0
	v_mov_b32_e32 v85, v0
	v_mov_b32_e32 v86, v0
	v_mov_b32_e32 v87, v0
	v_mov_b32_e32 v92, v0
	v_mov_b32_e32 v93, v0
	v_mov_b32_e32 v94, v0
	v_mov_b32_e32 v95, v0
	v_mov_b32_e32 v100, v0
	v_mov_b32_e32 v101, v0
	v_mov_b32_e32 v102, v0
	v_mov_b32_e32 v103, v0
	v_mov_b32_e32 v108, v0
	v_mov_b32_e32 v109, v0
	v_mov_b32_e32 v110, v0
	v_mov_b32_e32 v111, v0
	v_mov_b32_e32 v116, v0
	v_mov_b32_e32 v117, v0
	v_mov_b32_e32 v118, v0
	v_mov_b32_e32 v119, v0
	v_mov_b32_e32 v120, v0
	v_mov_b32_e32 v121, v0
	v_mov_b32_e32 v122, v0
	v_mov_b32_e32 v123, v0
	v_mov_b32_e32 v124, v0
	v_mov_b32_e32 v125, v0
	v_mov_b32_e32 v126, v0
	v_mov_b32_e32 v127, v0
	.p2alignl 6, 3212836864

; template <class Epi, class Sched>
; __device__ __forceinline__ void gemm_phase(LAS unsigned char* lds, const Gemm g, const Sched& S, const Epi& E) {
;     ...
;     for (;;) {
;         const bool has_next = S.next(ui + 1, nxt);
;         const char* nA = has_next ? (const char*)g.A + (size_t)nxt.pm * tA : cA; const char* nB = has_next ? (const char*)g.Bt + (size_t)nxt.pn * tB : cB;
;         for (int t = 0; t < nt; t += 2) {
;             const bool last = (t == nt - 2);
;             const char* a1 = cA + (size_t)(t + 1) * kstep;
;             const char* a2 = last ? nA : cA + (size_t)(t + 2) * kstep; const char* b2 = last ? nB : cB + (size_t)(t + 2) * kstep;
;     ...
;         for (int a = 0; a < 2; ++a)
; #pragma unroll
;             for (int b = 0; b < 2; ++b)
; #pragma unroll
;                 for (int m = 0; m < 4; ++m)
; #pragma unroll
;                     for (int n = 0; n < 2; ++n) acc[a][b][m][n] = (f32x4){0.f, 0.f, 0.f, 0.f};
;         cur = nxt; cA = nA; cB = nB; ++ui;
.LBB0_387:
	s_mov_b32 s16, s29
	s_mov_b32 s39, s29
	s_add_i32 s29, s29, 1
	s_cmp_lt_u32 s39, 9
	s_cselect_b64 s[14:15], -1, 0
	s_and_b64 s[12:13], s[14:15], exec
	s_cselect_b32 s12, s29, s16
	s_ashr_i32 s13, s12, 31
	s_lshl_b64 s[12:13], s[12:13], 19
	s_add_u32 s12, s0, s12
	s_addc_u32 s13, s1, s13
	s_and_b64 s[14:15], s[14:15], exec
	s_cselect_b32 s40, s13, s5
	s_cselect_b32 s41, s12, s4
	s_add_u32 s42, s4, 0x100
	v_mov_b32_e32 v0, 0
	s_addc_u32 s43, s5, 0
	s_mov_b32 s44, -2
	s_mov_b64 s[4:5], s[10:11]
	v_mov_b32_e32 v1, v0
	v_mov_b32_e32 v2, v0
	v_mov_b32_e32 v3, v0
	v_mov_b32_e32 v4, v0
	v_mov_b32_e32 v5, v0
	v_mov_b32_e32 v6, v0
	v_mov_b32_e32 v7, v0
	v_mov_b32_e32 v16, v0
	v_mov_b32_e32 v17, v0
	v_mov_b32_e32 v18, v0
	v_mov_b32_e32 v19, v0
	v_mov_b32_e32 v20, v0
	v_mov_b32_e32 v21, v0
	v_mov_b32_e32 v22, v0
	v_mov_b32_e32 v23, v0
	v_mov_b32_e32 v32, v0
	v_mov_b32_e32 v33, v0
	v_mov_b32_e32 v34, v0
	v_mov_b32_e32 v35, v0
	v_mov_b32_e32 v36, v0
	v_mov_b32_e32 v37, v0
	v_mov_b32_e32 v38, v0
	v_mov_b32_e32 v39, v0
	v_mov_b32_e32 v48, v0
	v_mov_b32_e32 v49, v0
	v_mov_b32_e32 v50, v0
	v_mov_b32_e32 v51, v0
	v_mov_b32_e32 v52, v0
	v_mov_b32_e32 v53, v0
	v_mov_b32_e32 v54, v0
	v_mov_b32_e32 v55, v0
	v_mov_b32_e32 v8, v0
	v_mov_b32_e32 v9, v0
	v_mov_b32_e32 v10, v0
	v_mov_b32_e32 v11, v0
	v_mov_b32_e32 v12, v0
	v_mov_b32_e32 v13, v0
	v_mov_b32_e32 v14, v0
	v_mov_b32_e32 v15, v0
	v_mov_b32_e32 v24, v0
	v_mov_b32_e32 v25, v0
	v_mov_b32_e32 v26, v0
	v_mov_b32_e32 v27, v0
	v_mov_b32_e32 v28, v0
	v_mov_b32_e32 v29, v0
	v_mov_b32_e32 v30, v0
	v_mov_b32_e32 v31, v0
	v_mov_b32_e32 v40, v0
	v_mov_b32_e32 v41, v0
	v_mov_b32_e32 v42, v0
	v_mov_b32_e32 v43, v0
	v_mov_b32_e32 v44, v0
	v_mov_b32_e32 v45, v0
	v_mov_b32_e32 v46, v0
	v_mov_b32_e32 v47, v0
	v_mov_b32_e32 v56, v0
	v_mov_b32_e32 v57, v0
	v_mov_b32_e32 v58, v0
	v_mov_b32_e32 v59, v0
	v_mov_b32_e32 v60, v0
	v_mov_b32_e32 v61, v0
	v_mov_b32_e32 v62, v0
	v_mov_b32_e32 v63, v0
	v_mov_b32_e32 v64, v0
	v_mov_b32_e32 v65, v0
	v_mov_b32_e32 v66, v0
	v_mov_b32_e32 v67, v0
	v_mov_b32_e32 v68, v0
	v_mov_b32_e32 v69, v0
	v_mov_b32_e32 v70, v0
	v_mov_b32_e32 v71, v0
	v_mov_b32_e32 v80, v0
	v_mov_b32_e32 v81, v0
	v_mov_b32_e32 v82, v0
	v_mov_b32_e32 v83, v0
	v_mov_b32_e32 v84, v0
	v_mov_b32_e32 v85, v0
	v_mov_b32_e32 v86, v0
	v_mov_b32_e32 v87, v0
	v_mov_b32_e32 v96, v0
	v_mov_b32_e32 v97, v0
	v_mov_b32_e32 v98, v0
	v_mov_b32_e32 v99, v0
	v_mov_b32_e32 v100, v0
	v_mov_b32_e32 v101, v0
	v_mov_b32_e32 v102, v0
	v_mov_b32_e32 v103, v0
	v_mov_b32_e32 v112, v0
	v_mov_b32_e32 v113, v0
	v_mov_b32_e32 v114, v0
	v_mov_b32_e32 v115, v0
	v_mov_b32_e32 v116, v0
	v_mov_b32_e32 v117, v0
	v_mov_b32_e32 v118, v0
	v_mov_b32_e32 v119, v0
	v_mov_b32_e32 v72, v0
	v_mov_b32_e32 v73, v0
	v_mov_b32_e32 v74, v0
	v_mov_b32_e32 v75, v0
	v_mov_b32_e32 v76, v0
	v_mov_b32_e32 v77, v0
	v_mov_b32_e32 v78, v0
	v_mov_b32_e32 v79, v0
	v_mov_b32_e32 v88, v0
	v_mov_b32_e32 v89, v0
	v_mov_b32_e32 v90, v0
	v_mov_b32_e32 v91, v0
	v_mov_b32_e32 v92, v0
	v_mov_b32_e32 v93, v0
	v_mov_b32_e32 v94, v0
	v_mov_b32_e32 v95, v0
	v_mov_b32_e32 v104, v0
	v_mov_b32_e32 v105, v0
	v_mov_b32_e32 v106, v0
	v_mov_b32_e32 v107, v0
	v_mov_b32_e32 v108, v0
	v_mov_b32_e32 v109, v0
	v_mov_b32_e32 v110, v0
	v_mov_b32_e32 v111, v0
	v_mov_b32_e32 v120, v0
	v_mov_b32_e32 v121, v0
	v_mov_b32_e32 v122, v0
	v_mov_b32_e32 v123, v0
	v_mov_b32_e32 v124, v0
	v_mov_b32_e32 v125, v0
	v_mov_b32_e32 v126, v0
	v_mov_b32_e32 v127, v0
	.p2alignl 6, 3212836864

; __device__ __forceinline__ int v_st(int k, int c) { const int kk = (k & ~0xC) | ((k & 4) << 1) | ((k & 8) >> 1); return ((kk >> 3) * 4 + (c >> 5)) * 512 + ((kk & 7) * 32 + (c & 31)) * 2; }
; __device__ __forceinline__ int v_rd_base(int lane) { return ((lane & 3) << 3) | (((lane >> 2) & 3) << 6) | (((lane >> 4) & 1) << 5) | (((lane >> 5) & 1) << 8); }
; #define SLOAD(i, k0) do { sr_[i].vs0 = LD8(&Vh[(long)((k0) + sr) * LDK + sc]); sr_[i].vs1 = LD8(&Vh[(long)((k0) + 32 + sr) * LDK + sc]); \
;     sr_[i].ks0 = LD8(&Kh[(long)((k0) + sr) * LDK + sc]); sr_[i].ks1 = LD8(&Kh[(long)((k0) + 32 + sr) * LDK + sc]); } while (0)
; #define SWRITE(b, i) do { *(bf16x8*)((char*)V_lds + (b) * SHM_V + vst0) = sr_[i].vs0;          \
;     *(bf16x8*)((char*)V_lds + (b) * SHM_V + vst1) = sr_[i].vs1; int kc = sc * 2;               \
;     *(bf16x8*)((char*)K_lds + (b) * SHM_K + KSWZ(sr, kc)) = sr_[i].ks0;                       \
;     *(bf16x8*)((char*)K_lds + (b) * SHM_K + KSWZ(32 + sr, kc)) = sr_[i].ks1; } while (0)
; __device__ __forceinline__ void attn_body(const bf16_t* __restrict__ Qb, const bf16_t* __restrict__ Kh, const bf16_t* __restrict__ Vh, const bf16_t* __restrict__ Zb, ...
;     ...
;     const int wid = tid >> 6, lane = tid & 63, r32 = lane & 31, hi = lane >> 5;
;     bf16_t* V_lds = (bf16_t*)lds; bf16_t* K_lds = (bf16_t*)(lds + 2 * SHM_V);
;     float* ws = (float*)(lds + 2 * SHM_V + 2 * SHM_K) + wid * 64; float* li_l = ws; float* al_l = ws + 32;
;     float l_reg = 0; f32x16 o[4] = {}; bf16x8 qr[8];
;     const bf16_t* Qw = Qb + (long)(wid * QBLK + r32) * LDQ + hi * 8;
; #pragma unroll
;     for (int d0 = 0; d0 < 8; ++d0) qr[d0] = *reinterpret_cast<const bf16x8*>(Qw + d0 * 16);
;     const int sr = tid >> 4, sc = (tid & 15) * 8, vst0 = v_st(sr, sc), vst1 = v_st(32 + sr, sc);
;     const int vb0 = (int)(uintptr_t)V_lds + v_rd_base(lane);
;     ...
;     f32x16 pA0, pA1, pB0, pB1; bf16x8 pa0, pa1, pa2, pa3; const int NT = seq / KVBLK;
;     constexpr int SE = 0, SO = 1;
;     asm volatile("s_waitcnt vmcnt(0)" ::: "memory"); SWRITE(0, SE); __syncthreads();
;     qkt(pA0, pA1, K_lds, qr, r32, hi); partialSM(pA0, pA1, negBC);
;     SLOAD(SE, 2 * KVBLK);
;     SWAIT(); SWRITE(1, SO); __syncthreads();
;     if (__builtin_amdgcn_readfirstlane(tid) >= 256) __builtin_amdgcn_s_setprio(1);
;     for (int j = 1; j + 1 < NT; j += 2) {
.LBB0_489:
	v_and_b32_e32 v203, 63, v200
	v_exp_f32_e32 v235, v1
	v_lshlrev_b32_e32 v1, 4, v203
	v_exp_f32_e32 v233, v0
	v_exp_f32_e32 v231, v2
	v_lshlrev_b32_e32 v0, 3, v203
	v_and_b32_e32 v1, 0xc0, v1
	v_lshlrev_b32_e32 v2, 1, v203
	v_and_or_b32 v1, v0, 24, v1
	v_and_b32_e32 v2, 32, v2
	v_and_b32_e32 v0, 0x100, v0
	s_cmp_lg_u32 0, -1
	v_or3_b32 v0, v1, v2, v0
	s_cselect_b32 s42, 0, 0
	s_mov_b32 s23, s9
	v_add_u32_e32 v206, s42, v0
	s_addk_i32 s42, 0x4000
	v_add_u32_e32 v205, s42, v0
	v_lshl_add_u64 v[0:1], v[186:187], 0, s[22:23]
	v_exp_f32_e32 v234, v3
	v_exp_f32_e32 v230, v4
	v_exp_f32_e32 v232, v5
	v_exp_f32_e32 v228, v6
	v_exp_f32_e32 v229, v7
	v_exp_f32_e32 v225, v8
	v_exp_f32_e32 v227, v9
	v_exp_f32_e32 v224, v10
	v_exp_f32_e32 v226, v11
	v_exp_f32_e32 v221, v12
	v_exp_f32_e32 v223, v13
	v_exp_f32_e32 v181, v14
	v_exp_f32_e32 v222, v15
	v_mad_u64_u32 v[2:3], s[22:23], v0, s30, 0
	v_and_b32_e32 v0, 15, v200
	v_lshlrev_b32_e32 v0, 4, v0
	v_mad_i32_i24 v1, v1, s30, v3
	v_or3_b32 v0, v2, s41, v0
	v_mov_b32_e32 v204, 0
	s_mov_b32 s39, 4
	s_add_i32 s40, s33, -1
	v_lshl_add_u64 v[190:191], s[12:13], 0, v[0:1]
	v_mov_b32_e32 v0, 0
	v_mov_b32_e32 v1, v204
	v_mov_b32_e32 v2, v204
	v_mov_b32_e32 v3, v204
	v_mov_b32_e32 v4, v204
	v_mov_b32_e32 v5, v204
	v_mov_b32_e32 v6, v204
	v_mov_b32_e32 v7, v204
	v_mov_b32_e32 v8, v204
	v_mov_b32_e32 v9, v204
	v_mov_b32_e32 v10, v204
	v_mov_b32_e32 v11, v204
	v_mov_b32_e32 v12, v204
	v_mov_b32_e32 v13, v204
	v_mov_b32_e32 v14, v204
	v_mov_b32_e32 v15, v204
	v_mov_b32_e32 v16, 0
	v_mov_b32_e32 v17, v204
	v_mov_b32_e32 v18, v204
	v_mov_b32_e32 v19, v204
	v_mov_b32_e32 v20, v204
	v_mov_b32_e32 v21, v204
	v_mov_b32_e32 v22, v204
	v_mov_b32_e32 v23, v204
	v_mov_b32_e32 v24, v204
	v_mov_b32_e32 v25, v204
	v_mov_b32_e32 v26, v204
	v_mov_b32_e32 v27, v204
	v_mov_b32_e32 v28, v204
	v_mov_b32_e32 v29, v204
	v_mov_b32_e32 v30, v204
	v_mov_b32_e32 v31, v204
	v_mov_b32_e32 v32, 0
	v_mov_b32_e32 v33, v204
	v_mov_b32_e32 v34, v204
	v_mov_b32_e32 v35, v204
	v_mov_b32_e32 v36, v204
	v_mov_b32_e32 v37, v204
	v_mov_b32_e32 v38, v204
	v_mov_b32_e32 v39, v204
	v_mov_b32_e32 v40, v204
	v_mov_b32_e32 v41, v204
	v_mov_b32_e32 v42, v204
	v_mov_b32_e32 v43, v204
	v_mov_b32_e32 v44, v204
	v_mov_b32_e32 v45, v204
	v_mov_b32_e32 v46, v204
	v_mov_b32_e32 v47, v204
	v_mov_b32_e32 v48, 0
	v_mov_b32_e32 v49, v204
	v_mov_b32_e32 v50, v204
	v_mov_b32_e32 v51, v204
	v_mov_b32_e32 v52, v204
	v_mov_b32_e32 v53, v204
	v_mov_b32_e32 v54, v204
	v_mov_b32_e32 v55, v204
	v_mov_b32_e32 v56, v204
	v_mov_b32_e32 v57, v204
	v_mov_b32_e32 v58, v204
	v_mov_b32_e32 v59, v204
	v_mov_b32_e32 v60, v204
	v_mov_b32_e32 v61, v204
	v_mov_b32_e32 v62, v204
	v_mov_b32_e32 v63, v204
	v_exp_f32_e32 v64, v64
	v_exp_f32_e32 v65, v65
	v_exp_f32_e32 v66, v66
	v_exp_f32_e32 v67, v67
	v_exp_f32_e32 v68, v68
	v_exp_f32_e32 v69, v69
	v_exp_f32_e32 v70, v70
	v_exp_f32_e32 v71, v71
	v_exp_f32_e32 v72, v72
	v_exp_f32_e32 v73, v73
	v_exp_f32_e32 v74, v74
	v_exp_f32_e32 v75, v75
	v_exp_f32_e32 v76, v76
	v_exp_f32_e32 v77, v77
	v_exp_f32_e32 v78, v78
	v_exp_f32_e32 v79, v79
	s_mov_b32 s100, 0xfffa0000
	s_mov_b32 s101, -1
	s_mov_b32 s98, 0xfffd0000
	s_mov_b32 s99, -1
	v_add_u32_e32 v252, 0x10000, v207
	v_add_u32_e32 v253, 0x10000, v208
	v_lshl_add_u64 v[190:191], v[190:191], 0, s[100:101]
	s_mov_b32 s100, 0x60000
	s_mov_b32 s101, 0
	.p2alignl 6, 3212836864

; template <class Epi, class Sched>
; __device__ __forceinline__ void gemm_phase(LAS unsigned char* lds, const Gemm g, const Sched& S, const Epi& E) {
;     ...
;     for (;;) {
;         const bool has_next = S.next(ui + 1, nxt);
;         const char* nA = has_next ? (const char*)g.A + (size_t)nxt.pm * tA : cA; const char* nB = has_next ? (const char*)g.Bt + (size_t)nxt.pn * tB : cB;
;         for (int t = 0; t < nt; t += 2) {
;             const bool last = (t == nt - 2);
;             const char* a1 = cA + (size_t)(t + 1) * kstep;
;             const char* a2 = last ? nA : cA + (size_t)(t + 2) * kstep; const char* b2 = last ? nB : cB + (size_t)(t + 2) * kstep;
;     ...
;         for (int a = 0; a < 2; ++a)
; #pragma unroll
;             for (int b = 0; b < 2; ++b)
; #pragma unroll
;                 for (int m = 0; m < 4; ++m)
; #pragma unroll
;                     for (int n = 0; n < 2; ++n) acc[a][b][m][n] = (f32x4){0.f, 0.f, 0.f, 0.f};
;         cur = nxt; cA = nA; cB = nB; ++ui;
.LBB0_554:
	s_mov_b32 s16, s37
	s_add_i32 s37, s38, 1
	s_cmp_lt_u32 s38, 3
	s_cselect_b64 s[14:15], -1, 0
	s_and_b64 s[10:11], s[14:15], exec
	s_cselect_b32 s10, s37, s16
	s_ashr_i32 s11, s10, 31
	s_lshl_b64 s[10:11], s[10:11], 19
	s_add_u32 s10, s4, s10
	s_addc_u32 s11, s5, s11
	s_and_b64 s[14:15], s[14:15], exec
	s_cselect_b32 s39, s11, s13
	s_cselect_b32 s40, s10, s12
	s_add_u32 s41, s12, 0x100
	v_mov_b32_e32 v0, 0
	s_addc_u32 s42, s13, 0
	s_mov_b32 s43, -2
	s_mov_b64 s[12:13], s[6:7]
	v_mov_b32_e32 v1, v0
	v_mov_b32_e32 v2, v0
	v_mov_b32_e32 v3, v0
	v_mov_b32_e32 v4, v0
	v_mov_b32_e32 v5, v0
	v_mov_b32_e32 v6, v0
	v_mov_b32_e32 v7, v0
	v_mov_b32_e32 v16, v0
	v_mov_b32_e32 v17, v0
	v_mov_b32_e32 v18, v0
	v_mov_b32_e32 v19, v0
	v_mov_b32_e32 v20, v0
	v_mov_b32_e32 v21, v0
	v_mov_b32_e32 v22, v0
	v_mov_b32_e32 v23, v0
	v_mov_b32_e32 v32, v0
	v_mov_b32_e32 v33, v0
	v_mov_b32_e32 v34, v0
	v_mov_b32_e32 v35, v0
	v_mov_b32_e32 v36, v0
	v_mov_b32_e32 v37, v0
	v_mov_b32_e32 v38, v0
	v_mov_b32_e32 v39, v0
	v_mov_b32_e32 v40, v0
	v_mov_b32_e32 v41, v0
	v_mov_b32_e32 v42, v0
	v_mov_b32_e32 v43, v0
	v_mov_b32_e32 v44, v0
	v_mov_b32_e32 v45, v0
	v_mov_b32_e32 v46, v0
	v_mov_b32_e32 v47, v0
	v_mov_b32_e32 v8, v0
	v_mov_b32_e32 v9, v0
	v_mov_b32_e32 v10, v0
	v_mov_b32_e32 v11, v0
	v_mov_b32_e32 v12, v0
	v_mov_b32_e32 v13, v0
	v_mov_b32_e32 v14, v0
	v_mov_b32_e32 v15, v0
	v_mov_b32_e32 v24, v0
	v_mov_b32_e32 v25, v0
	v_mov_b32_e32 v26, v0
	v_mov_b32_e32 v27, v0
	v_mov_b32_e32 v28, v0
	v_mov_b32_e32 v29, v0
	v_mov_b32_e32 v30, v0
	v_mov_b32_e32 v31, v0
	v_mov_b32_e32 v48, v0
	v_mov_b32_e32 v49, v0
	v_mov_b32_e32 v50, v0
	v_mov_b32_e32 v51, v0
	v_mov_b32_e32 v52, v0
	v_mov_b32_e32 v53, v0
	v_mov_b32_e32 v54, v0
	v_mov_b32_e32 v55, v0
	v_mov_b32_e32 v56, v0
	v_mov_b32_e32 v57, v0
	v_mov_b32_e32 v58, v0
	v_mov_b32_e32 v59, v0
	v_mov_b32_e32 v60, v0
	v_mov_b32_e32 v61, v0
	v_mov_b32_e32 v62, v0
	v_mov_b32_e32 v63, v0
	v_mov_b32_e32 v64, v0
	v_mov_b32_e32 v65, v0
	v_mov_b32_e32 v66, v0
	v_mov_b32_e32 v67, v0
	v_mov_b32_e32 v68, v0
	v_mov_b32_e32 v69, v0
	v_mov_b32_e32 v70, v0
	v_mov_b32_e32 v71, v0
	v_mov_b32_e32 v80, v0
	v_mov_b32_e32 v81, v0
	v_mov_b32_e32 v82, v0
	v_mov_b32_e32 v83, v0
	v_mov_b32_e32 v84, v0
	v_mov_b32_e32 v85, v0
	v_mov_b32_e32 v86, v0
	v_mov_b32_e32 v87, v0
	v_mov_b32_e32 v96, v0
	v_mov_b32_e32 v97, v0
	v_mov_b32_e32 v98, v0
	v_mov_b32_e32 v99, v0
	v_mov_b32_e32 v100, v0
	v_mov_b32_e32 v101, v0
	v_mov_b32_e32 v102, v0
	v_mov_b32_e32 v103, v0
	v_mov_b32_e32 v104, v0
	v_mov_b32_e32 v105, v0
	v_mov_b32_e32 v106, v0
	v_mov_b32_e32 v107, v0
	v_mov_b32_e32 v108, v0
	v_mov_b32_e32 v109, v0
	v_mov_b32_e32 v110, v0
	v_mov_b32_e32 v111, v0
	v_mov_b32_e32 v72, v0
	v_mov_b32_e32 v73, v0
	v_mov_b32_e32 v74, v0
	v_mov_b32_e32 v75, v0
	v_mov_b32_e32 v76, v0
	v_mov_b32_e32 v77, v0
	v_mov_b32_e32 v78, v0
	v_mov_b32_e32 v79, v0
	v_mov_b32_e32 v88, v0
	v_mov_b32_e32 v89, v0
	v_mov_b32_e32 v90, v0
	v_mov_b32_e32 v91, v0
	v_mov_b32_e32 v92, v0
	v_mov_b32_e32 v93, v0
	v_mov_b32_e32 v94, v0
	v_mov_b32_e32 v95, v0
	v_mov_b32_e32 v112, v0
	v_mov_b32_e32 v113, v0
	v_mov_b32_e32 v114, v0
	v_mov_b32_e32 v115, v0
	v_mov_b32_e32 v116, v0
	v_mov_b32_e32 v117, v0
	v_mov_b32_e32 v118, v0
	v_mov_b32_e32 v119, v0
	v_mov_b32_e32 v120, v0
	v_mov_b32_e32 v121, v0
	v_mov_b32_e32 v122, v0
	v_mov_b32_e32 v123, v0
	v_mov_b32_e32 v124, v0
	v_mov_b32_e32 v125, v0
	v_mov_b32_e32 v126, v0
	v_mov_b32_e32 v127, v0
	.p2alignl 6, 3212836864
